# LN1 row loop: restored the two wait states before a DPP read that a removed address add used to provide (hazard-clean build of the previous version)
# speedup vs baseline: 1.0118x; 1.0001x over previous
.Lln1_a1:
	v_pk_fma_f32 v[30:31], v[84:85], v[44:45], v[88:89]
	v_pk_mul_f32 v[34:35], v[46:47], v[60:61] op_sel_hi:[1,0]
	v_pk_mul_f32 v[50:51], v[50:51], v[60:61] op_sel_hi:[1,0]
	v_pk_fma_f32 v[32:33], v[86:87], v[34:35], v[90:91]
	global_store_dwordx4 v[12:13], v[30:33], off
	v_pk_mul_f32 v[52:53], v[52:53], v[60:61] op_sel_hi:[1,0]
	v_pk_mul_f32 v[54:55], v[54:55], v[60:61] op_sel_hi:[1,0]
	v_pk_mul_f32 v[56:57], v[56:57], v[60:61] op_sel_hi:[1,0]
	v_pk_mul_f32 v[58:59], v[58:59], v[60:61] op_sel_hi:[1,0]
	v_mov_b32_e32 v60, v30
	v_mov_b32_e32 v68, v31
	v_mov_b32_e32 v70, v32
	v_mov_b32_e32 v72, v33
	v_pk_fma_f32 v[34:35], v[92:93], v[48:49], v[96:97]
	v_pk_fma_f32 v[36:37], v[94:95], v[50:51], v[98:99]
	global_store_dwordx4 v[12:13], v[34:37], off offset:1024
	v_mov_b32_e32 v61, v34
	v_mov_b32_e32 v69, v35
	v_mov_b32_e32 v71, v36
	v_pk_add_f32 v[60:61], v[60:61], v[68:69]
	v_mov_b32_e32 v73, v37
	v_pk_add_f32 v[60:61], v[70:71], v[60:61]
	v_pk_fma_f32 v[44:45], v[52:53], v[100:101], v[104:105]
	v_pk_fma_f32 v[46:47], v[54:55], v[102:103], v[106:107]
	global_store_dwordx4 v[12:13], v[44:47], off offset:2048
	v_pk_add_f32 v[60:61], v[72:73], v[60:61]
	v_mov_b32_e32 v68, v45
	v_add_f32_e32 v28, 0, v60
	v_add_f32_e32 v28, v28, v61
	v_mov_b32_e32 v60, v44
	v_mov_b32_e32 v70, v46
	v_mov_b32_e32 v72, v47
	v_pk_fma_f32 v[48:49], v[56:57], v[108:109], v[112:113]
	v_pk_fma_f32 v[50:51], v[58:59], v[110:111], v[114:115]
	global_store_dwordx4 v[12:13], v[48:51], off offset:3072
	v_mov_b32_e32 v61, v48
	v_mov_b32_e32 v69, v49
	v_mov_b32_e32 v71, v50
	v_pk_add_f32 v[60:61], v[60:61], v[68:69]
	v_mov_b32_e32 v73, v51
	v_pk_add_f32 v[60:61], v[60:61], v[70:71]
	v_lshl_add_u64 v[12:13], v[12:13], 0, s[36:37]
	v_pk_add_f32 v[60:61], v[60:61], v[72:73]
	s_nop 0
	v_add_f32_e32 v28, v28, v60
	v_add_f32_e32 v28, v28, v61
	s_nop 1
	v_add_f32_dpp v28, v28, v28 quad_perm:[1,0,3,2] row_mask:0xf bank_mask:0xf bound_ctrl:1
	s_nop 1
	v_add_f32_dpp v28, v28, v28 quad_perm:[2,3,0,1] row_mask:0xf bank_mask:0xf bound_ctrl:1
	s_nop 1
	v_add_f32_dpp v28, v28, v28 row_half_mirror row_mask:0xf bank_mask:0xf bound_ctrl:1
	s_nop 1
	v_add_f32_dpp v28, v28, v28 row_mirror row_mask:0xf bank_mask:0xf bound_ctrl:1
	ds_bpermute_b32 v43, v29, v28
	s_waitcnt lgkmcnt(0)
	v_add_f32_e32 v28, v28, v43
	ds_bpermute_b32 v43, v41, v28
	s_waitcnt lgkmcnt(0)
	v_add_f32_e32 v28, v28, v43
	v_mul_f32_e32 v28, 0x3a800000, v28
	v_pk_add_f32 v[30:31], v[30:31], v[28:29] op_sel_hi:[1,0] neg_lo:[0,1] neg_hi:[0,1]
	v_pk_add_f32 v[66:67], v[34:35], v[28:29] op_sel_hi:[1,0] neg_lo:[0,1] neg_hi:[0,1]
	v_pk_add_f32 v[44:45], v[44:45], v[28:29] op_sel_hi:[1,0] neg_lo:[0,1] neg_hi:[0,1]
	v_pk_add_f32 v[68:69], v[50:51], v[28:29] op_sel_hi:[1,0] neg_lo:[0,1] neg_hi:[0,1]
	v_pk_add_f32 v[70:71], v[48:49], v[28:29] op_sel_hi:[1,0] neg_lo:[0,1] neg_hi:[0,1]
	v_mov_b32_e32 v50, v31
	v_mov_b32_e32 v51, v67
	v_pk_add_f32 v[32:33], v[32:33], v[28:29] op_sel_hi:[1,0] neg_lo:[0,1] neg_hi:[0,1]
	v_pk_add_f32 v[60:61], v[36:37], v[28:29] op_sel_hi:[1,0] neg_lo:[0,1] neg_hi:[0,1]
	v_mov_b32_e32 v48, v30
	v_mov_b32_e32 v49, v66
	v_mov_b32_e32 v78, v71
	v_mov_b32_e32 v79, v45
	v_pk_mul_f32 v[50:51], v[50:51], v[50:51]
	v_pk_add_f32 v[46:47], v[46:47], v[28:29] op_sel_hi:[1,0] neg_lo:[0,1] neg_hi:[0,1]
	v_mov_b32_e32 v34, v32
	v_mov_b32_e32 v35, v60
	v_mov_b32_e32 v76, v70
	v_mov_b32_e32 v77, v44
	v_pk_mul_f32 v[78:79], v[78:79], v[78:79]
	v_pk_fma_f32 v[48:49], v[48:49], v[48:49], v[50:51]
	v_mov_b32_e32 v36, v33
	v_mov_b32_e32 v37, v61
	v_mov_b32_e32 v72, v68
	v_mov_b32_e32 v73, v46
	v_pk_fma_f32 v[50:51], v[76:77], v[76:77], v[78:79]
	v_pk_fma_f32 v[34:35], v[34:35], v[34:35], v[48:49]
	v_mov_b32_e32 v74, v69
	v_mov_b32_e32 v75, v47
	v_pk_fma_f32 v[48:49], v[72:73], v[72:73], v[50:51]
	v_pk_fma_f32 v[34:35], v[36:37], v[36:37], v[34:35]
	v_pk_fma_f32 v[36:37], v[74:75], v[74:75], v[48:49]
	v_add_f32_e32 v28, v34, v35
	v_add_f32_e32 v28, v37, v28
	v_add_f32_e32 v28, v36, v28
	s_nop 0
	s_nop 0
	v_add_f32_dpp v28, v28, v28 quad_perm:[1,0,3,2] row_mask:0xf bank_mask:0xf bound_ctrl:1
	s_nop 1
	v_add_f32_dpp v28, v28, v28 quad_perm:[2,3,0,1] row_mask:0xf bank_mask:0xf bound_ctrl:1
	s_nop 1
	v_add_f32_dpp v28, v28, v28 row_half_mirror row_mask:0xf bank_mask:0xf bound_ctrl:1
	s_nop 1
	v_add_f32_dpp v28, v28, v28 row_mirror row_mask:0xf bank_mask:0xf bound_ctrl:1
	ds_bpermute_b32 v34, v29, v28
	s_waitcnt lgkmcnt(0)
	v_add_f32_e32 v28, v28, v34
	ds_bpermute_b32 v36, v41, v28
	v_lshl_add_u64 v[34:35], v[2:3], 0, v[0:1]
	v_add_co_u32_e64 v72, s[8:9], s43, v34
	v_lshl_add_u64 v[2:3], v[2:3], 0, s[34:35]
	s_waitcnt lgkmcnt(0)
	v_add_f32_e32 v28, v28, v36
	v_fmamk_f32 v28, v28, 0x3a800000, v38
	v_mul_f32_e32 v36, 0x4b800000, v28
	v_cmp_gt_f32_e32 vcc, s40, v28
	v_addc_co_u32_e64 v73, s[8:9], 0, v35, s[8:9]
	s_nop 0
	v_cndmask_b32_e32 v28, v28, v36, vcc
	v_rsq_f32_e32 v28, v28
	s_cmp_eq_u64 s[60:61], 0
	s_cbranch_scc1 .Lln1_b0
	s_waitcnt vmcnt(8)
	s_branch .Lln1_b1
